# static priority raise (s_setprio 1) for the second co-resident workgroup during attention phases 2 and 3
# baseline (speedup 1.0000x reference)
; DI int TIDX() { int t = threadIdx.x; asm volatile("" : "+v"(t)); return t; }
; DI float compute_lam(const Params& P, int l) {
;   const int lane = TIDX() & 63;
;   const float* lp = P.a_lambda + l * 256;
;   float a = lp[lane] * lp[64 + lane], b = lp[128 + lane] * lp[192 + lane];
; #pragma unroll
;   for (int o = 32; o > 0; o >>= 1) { a += __shfl_xor(a, o); b += __shfl_xor(b, o); }
;   return __expf(a) - __expf(b) + P.lam_init[l];
; }
;   unsigned* ctr = (unsigned*)(P.ws + OFF_CTR) + l * 4 + (dry ? 2 : 0);
;   bf16_t* Pb_ = (bf16_t*)(P.ws + OFF_P); bf16_t* xb_ = (bf16_t*)(P.ws + OFF_XB);
;   bf16_t* ya = dry ? xb_ : Pb_ + C_AQ; bf16_t* yb = dry ? xb_ + 512 : Pb_ + C_BQ; const size_t yp_ = dry ? 1024 : PW;
;   const float lam = compute_lam(P, l);
;   const int per = 16 + 16 + 32, total = 64 * per;
;   for (;;) {
;     const int it = next_item(ctr, smem);
.LBB0_748:
	s_or_b64 exec, exec, s[4:5]
	v_readlane_b32 s101, v253, 0
	s_bitcmp1_b32 s101, 8
	s_cbranch_scc0 .Lattnprio0
	s_setprio 1
.Lattnprio0:
	v_readlane_b32 s8, v252, 21
	s_lshl_b32 s26, s8, 2
	s_lshl_b64 s[4:5], s[26:27], 2
	v_readlane_b32 s1, v254, 32
	v_readlane_b32 s9, v252, 22
	s_add_u32 s6, s1, s4
	v_readlane_b32 s1, v254, 33
	v_writelane_b32 v252, s4, 23
	s_addc_u32 s7, s1, s5
	s_waitcnt lgkmcnt(0)
	v_mov_b32_e32 v0, v148
	v_writelane_b32 v252, s5, 24
	v_writelane_b32 v252, s6, 25
	s_lshl_b32 s26, s8, 8
	s_nop 0
	v_writelane_b32 v252, s7, 26
	s_barrier
	v_readlane_b32 s12, v252, 7
	s_lshl_b64 s[4:5], s[26:27], 2
	v_readlane_b32 s16, v252, 11
	v_and_b32_e32 v0, 63, v0
	v_readlane_b32 s17, v252, 12
	s_add_u32 s4, s16, s4
	s_addc_u32 s5, s17, s5
	v_lshlrev_b32_e32 v0, 2, v0
	global_load_dword v1, v0, s[4:5]
	global_load_dword v2, v0, s[4:5] offset:256
	global_load_dword v3, v0, s[4:5] offset:512
	s_nop 0
	global_load_dword v0, v0, s[4:5] offset:768
	v_and_b32_e32 v11, 15, v175
	v_cmp_ne_u32_e32 vcc, 15, v11
	v_bitop3_b32 v12, v175, 15, v175 bitop3:0xc
	v_and_b32_e32 v4, 64, v175
	v_addc_co_u32_e32 v11, vcc, 0, v175, vcc
	v_cmp_gt_u32_e32 vcc, 2, v12
	v_xor_b32_e32 v5, 32, v175
	v_add_u32_e32 v4, 64, v4
	v_cndmask_b32_e64 v13, 2, 0, vcc
	v_cmp_gt_u32_e32 vcc, 4, v12
	v_xor_b32_e32 v6, 16, v175
	v_xor_b32_e32 v7, 8, v175
	v_cndmask_b32_e64 v12, 4, 0, vcc
	v_cmp_lt_i32_e32 vcc, v5, v4
	v_xor_b32_e32 v8, 4, v175
	v_xor_b32_e32 v9, 2, v175
	v_cndmask_b32_e32 v5, v175, v5, vcc
	v_lshlrev_b32_e32 v188, 2, v5
	v_cmp_lt_i32_e32 vcc, v6, v4
	v_xor_b32_e32 v10, 1, v175
	v_cmp_eq_u32_e64 s[4:5], 0, v175
	v_cndmask_b32_e32 v6, v175, v6, vcc
	v_lshlrev_b32_e32 v189, 2, v6
	v_cmp_lt_i32_e32 vcc, v7, v4
	v_readlane_b32 s13, v252, 8
	v_readlane_b32 s14, v252, 9
	v_cndmask_b32_e32 v7, v175, v7, vcc
	v_cmp_lt_i32_e32 vcc, v8, v4
	v_readlane_b32 s15, v252, 10
	v_readlane_b32 s18, v252, 13
	v_cndmask_b32_e32 v8, v175, v8, vcc
	v_lshlrev_b32_e32 v6, 2, v8
	v_cmp_lt_i32_e32 vcc, v9, v4
	v_readlane_b32 s19, v252, 14
	v_writelane_b32 v252, s4, 27
	v_readlane_b32 s6, v253, 3
	v_readlane_b32 s7, v253, 4
	v_writelane_b32 v252, s5, 28
	s_lshl_b64 s[4:5], s[8:9], 2
	s_add_u32 s4, s6, s4
	s_addc_u32 s5, s7, s5
	v_writelane_b32 v252, s4, 29
	s_load_dword s1, s[4:5], 0x140
	s_lshl_b32 s26, s8, 7
	v_writelane_b32 v252, s5, 30
	s_lshl_b64 s[4:5], s[26:27], 2
	s_add_u32 s4, s18, s4
	s_addc_u32 s5, s19, s5
	v_lshlrev_b32_e32 v190, 2, v11
	v_add_lshl_u32 v191, v13, v175, 2
	v_add_lshl_u32 v192, v12, v175, 2
	v_writelane_b32 v252, s4, 31
	s_waitcnt vmcnt(2)
	v_mul_f32_e32 v5, v1, v2
	ds_bpermute_b32 v5, v188, v5
	s_waitcnt vmcnt(0)
	v_mul_f32_e32 v14, v3, v0
	ds_bpermute_b32 v14, v188, v14
	v_writelane_b32 v252, s5, 32
	s_waitcnt lgkmcnt(0)
	v_fmac_f32_e32 v5, v1, v2
	v_cndmask_b32_e32 v2, v175, v9, vcc
	v_fmac_f32_e32 v14, v3, v0
	ds_bpermute_b32 v0, v189, v5
	ds_bpermute_b32 v1, v189, v14
	v_lshlrev_b32_e32 v3, 2, v7
	v_lshlrev_b32_e32 v2, 2, v2
	v_cmp_lt_i32_e32 vcc, v10, v4
	s_waitcnt lgkmcnt(1)
	v_add_f32_e32 v0, v5, v0
	s_waitcnt lgkmcnt(0)
	v_add_f32_e32 v1, v14, v1
	ds_bpermute_b32 v5, v3, v0
	ds_bpermute_b32 v3, v3, v1
	v_cndmask_b32_e32 v4, v175, v10, vcc
	v_lshlrev_b32_e32 v4, 2, v4
	s_waitcnt lgkmcnt(1)
	v_add_f32_e32 v0, v0, v5
	s_waitcnt lgkmcnt(0)
	v_add_f32_e32 v1, v1, v3
	ds_bpermute_b32 v3, v6, v0
	ds_bpermute_b32 v5, v6, v1
	s_waitcnt lgkmcnt(1)
	v_add_f32_e32 v0, v0, v3
	s_waitcnt lgkmcnt(0)
	v_add_f32_e32 v1, v1, v5
	ds_bpermute_b32 v3, v2, v0
	ds_bpermute_b32 v2, v2, v1
	s_waitcnt lgkmcnt(1)
	v_add_f32_e32 v0, v0, v3
	s_waitcnt lgkmcnt(0)
	v_add_f32_e32 v1, v1, v2
	ds_bpermute_b32 v2, v4, v0
	ds_bpermute_b32 v3, v4, v1
	s_waitcnt lgkmcnt(1)
	v_add_f32_e32 v0, v0, v2
	s_waitcnt lgkmcnt(0)
	v_add_f32_e32 v1, v1, v3
	v_mul_f32_e32 v0, 0x3fb8aa3b, v0
	v_mul_f32_e32 v1, 0x3fb8aa3b, v1
	v_exp_f32_e32 v0, v0
	v_exp_f32_e32 v1, v1
	s_nop 0
	v_sub_f32_e32 v0, v0, v1
	v_add_f32_e32 v193, s1, v0
	s_branch .LBB0_752

; DI void xcd_barrier(const XcdBarrier& b) {
;   asm volatile("s_waitcnt vmcnt(0)" ::: "memory");
;   __syncthreads();
;   if (threadIdx.x == 0) {
;     unsigned* bar = b.bar;
;     __builtin_amdgcn_s_waitcnt(0);
;     unsigned nloc = b.st[0], nx = b.st[1];
;     if (nloc == 0u) { xcd_barrier_complete(bar, b.x, nloc, nx); b.st[0] = nloc; b.st[1] = nx; }
.LBB0_1015:
	s_waitcnt vmcnt(0)
	s_setprio 0
	s_waitcnt lgkmcnt(0)
	s_barrier
	s_mov_b64 s[4:5], exec
	v_readlane_b32 s6, v253, 7
	v_readlane_b32 s7, v253, 8
	s_and_b64 s[6:7], s[4:5], s[6:7]
	v_readlane_b32 s22, v254, 49
	s_movk_i32 s23, 0x70
	s_mov_b32 s24, 0x1ffffc0
	s_mov_b32 s20, 0x100000
	s_mov_b64 exec, s[6:7]
	s_cbranch_execz .LBB0_1067
	s_waitcnt vmcnt(0) expcnt(0) lgkmcnt(0)
	ds_read_b32 v2, v172
	ds_read_b32 v0, v173
	s_waitcnt lgkmcnt(1)
	v_cmp_ne_u32_e32 vcc, 0, v2
	s_cbranch_vccnz .LBB0_1031
	s_mov_b32 s1, 1
	s_branch .LBB0_1019

; DI int TIDX() { int t = threadIdx.x; asm volatile("" : "+v"(t)); return t; }
; DI int next_item(unsigned* ctr, char* smem) {
;   int* s = (int*)(smem + SMEM_BYTES);
;   __syncthreads();
;   if (TIDX() == 0) *s = (int)atomicAdd(ctr, 1u);
;   __syncthreads();
; DI void phase_attn2(const Params& P, int l, char* smem, bool dry) {
;   unsigned* ctr = (unsigned*)(P.ws + OFF_CTR) + l * 4 + (dry ? 3 : 1);
;   bf16_t* yc = dry ? (bf16_t*)(P.ws + OFF_XB) : (bf16_t*)(P.ws + OFF_P) + C_CQ; const size_t yp_ = dry ? 1024 : PW;
;   const int total = 32 * 32;
;   for (;;) {
;     const int it = next_item(ctr, smem);
.Lattnprio1:
	v_readlane_b32 s4, v254, 55
	v_readlane_b32 s5, v254, 56
	v_readlane_b32 s6, v254, 57
	v_readlane_b32 s4, v252, 23
	v_readlane_b32 s7, v254, 58
	v_readlane_b32 s5, v252, 24
	s_add_u32 s1, s6, s4
	s_addc_u32 s2, s7, s5
	s_add_u32 s4, s1, 0x1c800004
	s_addc_u32 s5, s2, 0
	s_waitcnt lgkmcnt(0)
	s_barrier
	s_branch .LBB0_1070

; DI void xcd_barrier(const XcdBarrier& b) {
;   asm volatile("s_waitcnt vmcnt(0)" ::: "memory");
;   __syncthreads();
;   if (threadIdx.x == 0) {
;     unsigned* bar = b.bar;
;     __builtin_amdgcn_s_waitcnt(0);
;     unsigned nloc = b.st[0], nx = b.st[1];
;     if (nloc == 0u) { xcd_barrier_complete(bar, b.x, nloc, nx); b.st[0] = nloc; b.st[1] = nx; }
.LBB0_1087:
	s_waitcnt vmcnt(0)
	s_setprio 0
	s_barrier
	s_mov_b64 s[4:5], exec
	v_readlane_b32 s6, v253, 7
	v_readlane_b32 s7, v253, 8
	s_and_b64 s[6:7], s[4:5], s[6:7]
	s_mov_b64 exec, s[6:7]
	s_cbranch_execz .LBB0_1139
	s_waitcnt vmcnt(0) expcnt(0) lgkmcnt(0)
	ds_read_b32 v2, v172
	ds_read_b32 v0, v173
	s_waitcnt lgkmcnt(1)
	v_cmp_ne_u32_e32 vcc, 0, v2
	s_cbranch_vccnz .LBB0_1103
	s_mov_b32 s1, 1
	s_branch .LBB0_1091
